# barrier hop removal: non-leader workgroups poll the cross-XCD release word TOPGEN directly instead of the per-XCC forwarded XGEN
# speedup vs baseline: 1.0023x; 1.0023x over previous
; __device__ __forceinline__ unsigned xb_ld(unsigned* p)              { return __hip_atomic_load(p, __ATOMIC_RELAXED, __HIP_MEMORY_SCOPE_AGENT); }
; __device__ __forceinline__ unsigned xb_add(unsigned* p, unsigned v) { return __hip_atomic_fetch_add(p, v, __ATOMIC_RELAXED, __HIP_MEMORY_SCOPE_AGENT); }
; #define XB_SPIN(cond, bar) do { unsigned _sp = 0; while (cond) { __builtin_amdgcn_s_sleep(1); \
;     if ((++_sp & 255u) == 0u) { if (xb_ld(&(bar)[XB_TMO])) break; if (_sp > XB_SPIN_CAP) { atomicAdd(&(bar)[XB_TMO], 1u); break; } } } } while (0)
; __device__ __forceinline__ void xcd_barrier(const XcdBarrier& b) {
;     ...
;         const unsigned old = xb_add(&bar[XB_XSUB(b.x)], 1u);
;         const unsigned gen = old / nloc;
;         if (old + 1u == (gen + 1u) * nloc) {
;             __builtin_amdgcn_fence(__ATOMIC_RELEASE, "agent");
;             asm volatile("s_waitcnt vmcnt(0)" ::: "memory");
;             const unsigned og = xb_add(&bar[XB_TOP], 1u);
;             const unsigned tg = og / nx;
;             if (og + 1u == (tg + 1u) * nx) xb_add(&bar[XB_TOPGEN], 1u);
;             else XB_SPIN(xb_ld(&bar[XB_TOPGEN]) == tg, bar);
;             __builtin_amdgcn_fence(__ATOMIC_ACQUIRE, "agent");
;             xb_add(&bar[XB_XGEN(b.x)], 1u);
;             asm volatile("s_waitcnt vmcnt(0)" ::: "memory");
;         } else {
;             XB_SPIN(xb_ld(&bar[XB_XGEN(b.x)]) == gen, bar);
.LBB0_72:
	s_or_b64 exec, exec, s[8:9]
	v_cvt_f32_u32_e32 v4, v2
	s_waitcnt vmcnt(0)
	v_readfirstlane_b32 s6, v3
	v_sub_u32_e32 v3, 0, v2
	v_rcp_iflag_f32_e32 v4, v4
	v_add_u32_e32 v5, s6, v1
	v_mul_f32_e32 v4, 0x4f7ffffe, v4
	v_cvt_u32_f32_e32 v4, v4
	v_mul_lo_u32 v1, v3, v4
	v_mul_hi_u32 v1, v4, v1
	v_add_u32_e32 v1, v4, v1
	v_mul_hi_u32 v1, v5, v1
	v_mul_lo_u32 v3, v1, v2
	v_sub_u32_e32 v3, v5, v3
	v_add_u32_e32 v4, 1, v1
	v_cmp_ge_u32_e32 vcc, v3, v2
	s_nop 1
	v_cndmask_b32_e32 v1, v1, v4, vcc
	v_sub_u32_e32 v4, v3, v2
	v_cndmask_b32_e32 v3, v3, v4, vcc
	v_add_u32_e32 v4, 1, v1
	v_cmp_ge_u32_e32 vcc, v3, v2
	v_add_u32_e32 v3, 1, v5
	s_nop 0
	v_cndmask_b32_e32 v1, v1, v4, vcc
	v_mul_lo_u32 v4, v2, v1
	v_add_u32_e32 v2, v4, v2
	v_cmp_ne_u32_e32 vcc, v3, v2
	s_and_saveexec_b64 s[6:7], vcc
	s_xor_b64 s[6:7], exec, s[6:7]
	s_cbranch_execz .LBB0_86
	s_waitcnt lgkmcnt(0)
	v_mov_b32_e32 v0, 0x2000
	s_add_u32 s12, s2, 0x81100
	s_addc_u32 s13, s3, 0
	global_load_dword v0, v0, s[12:13] offset:1024 sc1
	s_add_u32 s12, s2, 0x83500
	s_addc_u32 s13, s3, 0
	s_waitcnt vmcnt(0)
	v_cmp_eq_u32_e32 vcc, v0, v1
	s_and_saveexec_b64 s[8:9], vcc
	s_cbranch_execz .LBB0_85
	s_add_u32 s10, s2, 0x80200
	s_addc_u32 s11, s3, 0
	s_mov_b32 s24, 1
	s_mov_b64 s[14:15], 0
	v_mov_b32_e32 v0, 0
	s_branch .LBB0_76

; __device__ __forceinline__ unsigned xb_ld(unsigned* p)              { return __hip_atomic_load(p, __ATOMIC_RELAXED, __HIP_MEMORY_SCOPE_AGENT); }
; __device__ __forceinline__ unsigned xb_add(unsigned* p, unsigned v) { return __hip_atomic_fetch_add(p, v, __ATOMIC_RELAXED, __HIP_MEMORY_SCOPE_AGENT); }
; #define XB_SPIN(cond, bar) do { unsigned _sp = 0; while (cond) { __builtin_amdgcn_s_sleep(1); \
;     if ((++_sp & 255u) == 0u) { if (xb_ld(&(bar)[XB_TMO])) break; if (_sp > XB_SPIN_CAP) { atomicAdd(&(bar)[XB_TMO], 1u); break; } } } } while (0)
; __device__ __forceinline__ void xcd_barrier(const XcdBarrier& b) {
;     ...
;         const unsigned old = xb_add(&bar[XB_XSUB(b.x)], 1u);
;         const unsigned gen = old / nloc;
;         if (old + 1u == (gen + 1u) * nloc) {
;             __builtin_amdgcn_fence(__ATOMIC_RELEASE, "agent");
;             asm volatile("s_waitcnt vmcnt(0)" ::: "memory");
;             const unsigned og = xb_add(&bar[XB_TOP], 1u);
;             const unsigned tg = og / nx;
;             if (og + 1u == (tg + 1u) * nx) xb_add(&bar[XB_TOPGEN], 1u);
;             else XB_SPIN(xb_ld(&bar[XB_TOPGEN]) == tg, bar);
;             __builtin_amdgcn_fence(__ATOMIC_ACQUIRE, "agent");
;             xb_add(&bar[XB_XGEN(b.x)], 1u);
;             asm volatile("s_waitcnt vmcnt(0)" ::: "memory");
;         } else {
;             XB_SPIN(xb_ld(&bar[XB_XGEN(b.x)]) == gen, bar);
.LBB0_215:
	s_or_b64 exec, exec, s[8:9]
	v_cvt_f32_u32_e32 v4, v2
	s_waitcnt vmcnt(0)
	v_readfirstlane_b32 s6, v3
	v_sub_u32_e32 v3, 0, v2
	v_rcp_iflag_f32_e32 v4, v4
	v_add_u32_e32 v5, s6, v1
	v_mul_f32_e32 v4, 0x4f7ffffe, v4
	v_cvt_u32_f32_e32 v4, v4
	v_mul_lo_u32 v1, v3, v4
	v_mul_hi_u32 v1, v4, v1
	v_add_u32_e32 v1, v4, v1
	v_mul_hi_u32 v1, v5, v1
	v_mul_lo_u32 v3, v1, v2
	v_sub_u32_e32 v3, v5, v3
	v_add_u32_e32 v4, 1, v1
	v_cmp_ge_u32_e32 vcc, v3, v2
	s_nop 1
	v_cndmask_b32_e32 v1, v1, v4, vcc
	v_sub_u32_e32 v4, v3, v2
	v_cndmask_b32_e32 v3, v3, v4, vcc
	v_add_u32_e32 v4, 1, v1
	v_cmp_ge_u32_e32 vcc, v3, v2
	v_add_u32_e32 v3, 1, v5
	s_nop 0
	v_cndmask_b32_e32 v1, v1, v4, vcc
	v_mul_lo_u32 v4, v2, v1
	v_add_u32_e32 v2, v4, v2
	v_cmp_ne_u32_e32 vcc, v3, v2
	s_and_saveexec_b64 s[6:7], vcc
	s_xor_b64 s[6:7], exec, s[6:7]
	s_cbranch_execz .LBB0_229
	s_waitcnt lgkmcnt(0)
	s_add_u32 s12, s2, 0x81100
	s_addc_u32 s13, s3, 0
	global_load_dword v0, v237, s[12:13] offset:1024 sc1
	s_add_u32 s12, s2, 0x83500
	s_addc_u32 s13, s3, 0
	s_waitcnt vmcnt(0)
	v_cmp_eq_u32_e32 vcc, v0, v1
	s_and_saveexec_b64 s[8:9], vcc
	s_cbranch_execz .LBB0_228
	s_add_u32 s10, s2, 0x80200
	s_mov_b64 s[26:27], s[24:25]
	s_addc_u32 s11, s3, 0
	s_mov_b32 s24, 1
	s_mov_b64 s[14:15], 0
	s_branch .LBB0_219

; __device__ __forceinline__ unsigned xb_ld(unsigned* p)              { return __hip_atomic_load(p, __ATOMIC_RELAXED, __HIP_MEMORY_SCOPE_AGENT); }
; __device__ __forceinline__ unsigned xb_add(unsigned* p, unsigned v) { return __hip_atomic_fetch_add(p, v, __ATOMIC_RELAXED, __HIP_MEMORY_SCOPE_AGENT); }
; #define XB_SPIN(cond, bar) do { unsigned _sp = 0; while (cond) { __builtin_amdgcn_s_sleep(1); \
;     if ((++_sp & 255u) == 0u) { if (xb_ld(&(bar)[XB_TMO])) break; if (_sp > XB_SPIN_CAP) { atomicAdd(&(bar)[XB_TMO], 1u); break; } } } } while (0)
; __device__ __forceinline__ void xcd_barrier(const XcdBarrier& b) {
;     ...
;         const unsigned old = xb_add(&bar[XB_XSUB(b.x)], 1u);
;         const unsigned gen = old / nloc;
;         if (old + 1u == (gen + 1u) * nloc) {
;             __builtin_amdgcn_fence(__ATOMIC_RELEASE, "agent");
;             asm volatile("s_waitcnt vmcnt(0)" ::: "memory");
;             const unsigned og = xb_add(&bar[XB_TOP], 1u);
;             const unsigned tg = og / nx;
;             if (og + 1u == (tg + 1u) * nx) xb_add(&bar[XB_TOPGEN], 1u);
;             else XB_SPIN(xb_ld(&bar[XB_TOPGEN]) == tg, bar);
;             __builtin_amdgcn_fence(__ATOMIC_ACQUIRE, "agent");
;             xb_add(&bar[XB_XGEN(b.x)], 1u);
;             asm volatile("s_waitcnt vmcnt(0)" ::: "memory");
;         } else {
;             XB_SPIN(xb_ld(&bar[XB_XGEN(b.x)]) == gen, bar);
.LBB0_351:
	s_or_b64 exec, exec, s[10:11]
	v_cvt_f32_u32_e32 v4, v2
	s_waitcnt vmcnt(0)
	v_readfirstlane_b32 s8, v3
	v_sub_u32_e32 v3, 0, v2
	v_rcp_iflag_f32_e32 v4, v4
	v_add_u32_e32 v5, s8, v1
	v_mul_f32_e32 v4, 0x4f7ffffe, v4
	v_cvt_u32_f32_e32 v4, v4
	v_mul_lo_u32 v1, v3, v4
	v_mul_hi_u32 v1, v4, v1
	v_add_u32_e32 v1, v4, v1
	v_mul_hi_u32 v1, v5, v1
	v_mul_lo_u32 v3, v1, v2
	v_sub_u32_e32 v3, v5, v3
	v_add_u32_e32 v4, 1, v1
	v_cmp_ge_u32_e32 vcc, v3, v2
	s_nop 1
	v_cndmask_b32_e32 v1, v1, v4, vcc
	v_sub_u32_e32 v4, v3, v2
	v_cndmask_b32_e32 v3, v3, v4, vcc
	v_add_u32_e32 v4, 1, v1
	v_cmp_ge_u32_e32 vcc, v3, v2
	v_add_u32_e32 v3, 1, v5
	s_nop 0
	v_cndmask_b32_e32 v1, v1, v4, vcc
	v_mul_lo_u32 v4, v2, v1
	v_add_u32_e32 v2, v4, v2
	v_cmp_ne_u32_e32 vcc, v3, v2
	s_and_saveexec_b64 s[8:9], vcc
	s_xor_b64 s[8:9], exec, s[8:9]
	s_cbranch_execz .LBB0_365
	s_waitcnt lgkmcnt(0)
	s_add_u32 s14, s4, 0x81100
	s_addc_u32 s15, s5, 0
	global_load_dword v0, v237, s[14:15] offset:1024 sc1
	s_add_u32 s14, s4, 0x83500
	s_addc_u32 s15, s5, 0
	s_waitcnt vmcnt(0)
	v_cmp_eq_u32_e32 vcc, v0, v1
	s_and_saveexec_b64 s[10:11], vcc
	s_cbranch_execz .LBB0_364
	s_add_u32 s12, s4, 0x80200
	s_addc_u32 s13, s5, 0
	s_mov_b32 s26, 1
	s_mov_b64 s[16:17], 0
	s_branch .LBB0_355

; __device__ __forceinline__ unsigned xb_ld(unsigned* p)              { return __hip_atomic_load(p, __ATOMIC_RELAXED, __HIP_MEMORY_SCOPE_AGENT); }
; __device__ __forceinline__ unsigned xb_add(unsigned* p, unsigned v) { return __hip_atomic_fetch_add(p, v, __ATOMIC_RELAXED, __HIP_MEMORY_SCOPE_AGENT); }
; #define XB_SPIN(cond, bar) do { unsigned _sp = 0; while (cond) { __builtin_amdgcn_s_sleep(1); \
;     if ((++_sp & 255u) == 0u) { if (xb_ld(&(bar)[XB_TMO])) break; if (_sp > XB_SPIN_CAP) { atomicAdd(&(bar)[XB_TMO], 1u); break; } } } } while (0)
; __device__ __forceinline__ void xcd_barrier(const XcdBarrier& b) {
;     ...
;         const unsigned old = xb_add(&bar[XB_XSUB(b.x)], 1u);
;         const unsigned gen = old / nloc;
;         if (old + 1u == (gen + 1u) * nloc) {
;             __builtin_amdgcn_fence(__ATOMIC_RELEASE, "agent");
;             asm volatile("s_waitcnt vmcnt(0)" ::: "memory");
;             const unsigned og = xb_add(&bar[XB_TOP], 1u);
;             const unsigned tg = og / nx;
;             if (og + 1u == (tg + 1u) * nx) xb_add(&bar[XB_TOPGEN], 1u);
;             else XB_SPIN(xb_ld(&bar[XB_TOPGEN]) == tg, bar);
;             __builtin_amdgcn_fence(__ATOMIC_ACQUIRE, "agent");
;             xb_add(&bar[XB_XGEN(b.x)], 1u);
;             asm volatile("s_waitcnt vmcnt(0)" ::: "memory");
;         } else {
;             XB_SPIN(xb_ld(&bar[XB_XGEN(b.x)]) == gen, bar);
.LBB0_484:
	s_or_b64 exec, exec, s[8:9]
	v_cvt_f32_u32_e32 v4, v2
	s_waitcnt vmcnt(0)
	v_readfirstlane_b32 s6, v3
	v_sub_u32_e32 v3, 0, v2
	v_rcp_iflag_f32_e32 v4, v4
	v_add_u32_e32 v5, s6, v1
	v_mul_f32_e32 v4, 0x4f7ffffe, v4
	v_cvt_u32_f32_e32 v4, v4
	v_mul_lo_u32 v1, v3, v4
	v_mul_hi_u32 v1, v4, v1
	v_add_u32_e32 v1, v4, v1
	v_mul_hi_u32 v1, v5, v1
	v_mul_lo_u32 v3, v1, v2
	v_sub_u32_e32 v3, v5, v3
	v_add_u32_e32 v4, 1, v1
	v_cmp_ge_u32_e32 vcc, v3, v2
	s_nop 1
	v_cndmask_b32_e32 v1, v1, v4, vcc
	v_sub_u32_e32 v4, v3, v2
	v_cndmask_b32_e32 v3, v3, v4, vcc
	v_add_u32_e32 v4, 1, v1
	v_cmp_ge_u32_e32 vcc, v3, v2
	v_add_u32_e32 v3, 1, v5
	s_nop 0
	v_cndmask_b32_e32 v1, v1, v4, vcc
	v_mul_lo_u32 v4, v2, v1
	v_add_u32_e32 v2, v4, v2
	v_cmp_ne_u32_e32 vcc, v3, v2
	s_and_saveexec_b64 s[6:7], vcc
	s_xor_b64 s[6:7], exec, s[6:7]
	s_cbranch_execz .LBB0_498
	s_waitcnt lgkmcnt(0)
	s_add_u32 s12, s2, 0x81100
	s_addc_u32 s13, s3, 0
	global_load_dword v0, v237, s[12:13] offset:1024 sc1
	s_add_u32 s12, s2, 0x83500
	s_addc_u32 s13, s3, 0
	s_waitcnt vmcnt(0)
	v_cmp_eq_u32_e32 vcc, v0, v1
	s_and_saveexec_b64 s[8:9], vcc
	s_cbranch_execz .LBB0_497
	s_add_u32 s10, s2, 0x80200
	s_addc_u32 s11, s3, 0
	s_mov_b32 s24, 1
	s_mov_b64 s[14:15], 0
	s_branch .LBB0_488
